# plus static s_setprio 1 for the lagging wave group (waves 4-7) inside every staggered GEMM loop
# baseline (speedup 1.0000x reference)
.LBB0_55:
	v_mov_b32_e32 v137, v200
	s_lshl_b32 s25, s52, 3
	v_ashrrev_i32_e32 v14, 6, v137
	v_bfe_u32 v4, v137, 2, 4
	v_lshlrev_b32_e32 v5, 5, v14
	v_or_b32_e32 v6, v5, v4
	v_ashrrev_i32_e32 v7, 31, v6
	s_sub_i32 s25, s24, s25
	s_lshl_b64 s[36:37], s[28:29], 13
	v_lshrrev_b32_e32 v0, 4, v137
	v_lshlrev_b64 v[8:9], 13, v[6:7]
	v_or_b32_e32 v6, 16, v6
	s_waitcnt lgkmcnt(0)
	s_add_u32 s28, s34, s36
	v_xor_b32_e32 v0, v0, v137
	v_ashrrev_i32_e32 v7, 31, v6
	s_addc_u32 s29, s35, s37
	v_lshlrev_b32_e32 v2, 4, v0
	v_lshlrev_b64 v[6:7], 13, v[6:7]
	v_lshl_add_u64 v[8:9], s[28:29], 0, v[8:9]
	v_and_b32_e32 v2, 48, v2
	v_lshl_add_u64 v[6:7], s[28:29], 0, v[6:7]
	s_lshl_b32 s28, s25, 7
	v_lshl_add_u64 v[10:11], v[6:7], 0, v[2:3]
	v_lshlrev_b32_e32 v6, 4, v14
	v_or_b32_e32 v7, s28, v4
	v_add_u32_e32 v12, v7, v6
	v_ashrrev_i32_e32 v13, 31, v12
	v_lshlrev_b64 v[12:13], 13, v[12:13]
	v_and_b32_e32 v1, 63, v137
	v_lshl_add_u64 v[12:13], s[50:51], 0, v[12:13]
	v_lshl_add_u64 v[8:9], v[8:9], 0, v[2:3]
	v_lshl_add_u64 v[12:13], v[12:13], 0, v[2:3]
	v_lshlrev_b32_e32 v2, 4, v1
	v_lshl_or_b32 v138, v14, 11, v2
	v_lshl_or_b32 v139, v14, 10, v2
	v_add_u32_e32 v7, 16, v138
	v_add_u32_e32 v14, 0x400, v7
	v_readfirstlane_b32 s25, v7
	v_add_u32_e32 v16, 16, v139
	s_mov_b32 m0, s25
	v_readfirstlane_b32 s25, v14
	v_add_u32_e32 v14, 0x4000, v16
	global_load_lds_dwordx4 v[8:9], off
	s_mov_b32 m0, s25
	v_readfirstlane_b32 s25, v14
	v_add_u32_e32 v17, 0x6000, v7
	global_load_lds_dwordx4 v[10:11], off
	s_mov_b32 m0, s25
	v_readfirstlane_b32 s25, v17
	v_add_u32_e32 v17, 0x6400, v7
	global_load_lds_dwordx4 v[12:13], off
	v_lshl_add_u64 v[14:15], v[8:9], 0, 64
	s_mov_b32 m0, s25
	v_readfirstlane_b32 s25, v17
	v_add_u32_e32 v16, 0xa000, v16
	global_load_lds_dwordx4 v[14:15], off
	v_lshl_add_u64 v[14:15], v[10:11], 0, 64
	s_mov_b32 m0, s25
	v_readfirstlane_b32 s25, v16
	v_add_u32_e32 v16, 0xc000, v7
	global_load_lds_dwordx4 v[14:15], off
	v_lshl_add_u64 v[14:15], v[12:13], 0, 64
	s_mov_b32 m0, s25
	v_readfirstlane_b32 s25, v16
	v_add_u32_e32 v7, 0xc400, v7
	global_load_lds_dwordx4 v[14:15], off
	v_lshl_add_u64 v[14:15], v[8:9], 0, s[92:93]
	s_mov_b32 m0, s25
	v_readfirstlane_b32 s25, v7
	v_add_u32_e32 v2, 0x4000, v139
	global_load_lds_dwordx4 v[14:15], off
	s_mov_b32 m0, s25
	s_add_i32 s25, 16, 0xc000
	v_add_u32_e32 v7, s25, v2
	v_readlane_b32 s29, v235, 50
	v_lshl_add_u64 v[14:15], v[10:11], 0, s[92:93]
	v_readfirstlane_b32 s25, v7
	v_add_u32_e32 v7, s29, v138
	global_load_lds_dwordx4 v[14:15], off
	v_lshl_add_u64 v[14:15], v[12:13], 0, s[92:93]
	s_mov_b32 m0, s25
	v_readfirstlane_b32 s25, v7
	v_add_u32_e32 v7, 0x400, v7
	global_load_lds_dwordx4 v[14:15], off
	v_lshl_add_u64 v[8:9], v[8:9], 0, s[2:3]
	s_mov_b32 m0, s25
	v_readfirstlane_b32 s25, v7
	v_add_u32_e32 v2, s29, v2
	global_load_lds_dwordx4 v[8:9], off
	v_lshl_add_u64 v[8:9], v[10:11], 0, s[2:3]
	s_mov_b32 m0, s25
	v_readfirstlane_b32 s25, v2
	global_load_lds_dwordx4 v[8:9], off
	v_lshl_add_u64 v[8:9], v[12:13], 0, s[2:3]
	s_mov_b32 m0, s25
	v_readfirstlane_b32 s25, v137
	global_load_lds_dwordx4 v[8:9], off
	s_waitcnt vmcnt(6)
	s_and_b32 s29, s25, 0xffffff00
	s_cmpk_lg_i32 s29, 0x100
	s_barrier
	s_cbranch_scc1 .LBB0_57
	s_barrier
	s_setprio 1

.LBB0_65:
	s_setprio 0
	s_cmpk_lt_u32 s25, 0x100
	s_cbranch_scc0 .LBB0_50
	s_barrier
	s_branch .LBB0_50

.LBB0_76:
	v_mov_b32_e32 v137, v200
	s_lshl_b64 s[30:31], s[90:91], 13
	v_ashrrev_i32_e32 v14, 6, v137
	v_bfe_u32 v4, v137, 2, 4
	v_lshlrev_b32_e32 v5, 5, v14
	v_or_b32_e32 v6, v5, v4
	v_ashrrev_i32_e32 v7, 31, v6
	v_lshrrev_b32_e32 v0, 4, v137
	v_lshlrev_b64 v[8:9], 13, v[6:7]
	v_or_b32_e32 v6, 16, v6
	s_waitcnt lgkmcnt(0)
	s_add_u32 s36, s28, s30
	v_xor_b32_e32 v0, v0, v137
	v_ashrrev_i32_e32 v7, 31, v6
	s_addc_u32 s37, s29, s31
	v_lshlrev_b32_e32 v2, 4, v0
	v_lshlrev_b64 v[6:7], 13, v[6:7]
	s_lshl_b32 s34, s25, 7
	v_and_b32_e32 v2, 48, v2
	v_lshl_add_u64 v[6:7], s[36:37], 0, v[6:7]
	s_and_b32 s34, s34, 0x380
	v_lshl_add_u64 v[10:11], v[6:7], 0, v[2:3]
	v_lshlrev_b32_e32 v6, 4, v14
	v_or_b32_e32 v7, s34, v4
	v_add_u32_e32 v12, v7, v6
	v_ashrrev_i32_e32 v13, 31, v12
	v_lshlrev_b64 v[12:13], 13, v[12:13]
	v_and_b32_e32 v1, 63, v137
	v_lshl_add_u64 v[8:9], s[36:37], 0, v[8:9]
	v_lshl_add_u64 v[12:13], s[50:51], 0, v[12:13]
	v_lshl_add_u64 v[8:9], v[8:9], 0, v[2:3]
	v_lshl_add_u64 v[12:13], v[12:13], 0, v[2:3]
	v_lshlrev_b32_e32 v2, 4, v1
	v_lshl_or_b32 v138, v14, 11, v2
	v_lshl_or_b32 v139, v14, 10, v2
	v_add_u32_e32 v7, 16, v138
	v_add_u32_e32 v14, 0x400, v7
	v_readfirstlane_b32 s36, v7
	v_add_u32_e32 v16, 16, v139
	s_mov_b32 m0, s36
	v_readfirstlane_b32 s36, v14
	v_add_u32_e32 v14, 0x4000, v16
	global_load_lds_dwordx4 v[8:9], off
	s_mov_b32 m0, s36
	v_readfirstlane_b32 s36, v14
	v_add_u32_e32 v17, 0x6000, v7
	global_load_lds_dwordx4 v[10:11], off
	s_mov_b32 m0, s36
	v_readfirstlane_b32 s36, v17
	v_add_u32_e32 v17, 0x6400, v7
	global_load_lds_dwordx4 v[12:13], off
	v_lshl_add_u64 v[14:15], v[8:9], 0, 64
	s_mov_b32 m0, s36
	v_readfirstlane_b32 s36, v17
	v_add_u32_e32 v16, 0xa000, v16
	global_load_lds_dwordx4 v[14:15], off
	v_lshl_add_u64 v[14:15], v[10:11], 0, 64
	s_mov_b32 m0, s36
	v_readfirstlane_b32 s36, v16
	v_add_u32_e32 v16, 0xc000, v7
	global_load_lds_dwordx4 v[14:15], off
	v_lshl_add_u64 v[14:15], v[12:13], 0, 64
	s_mov_b32 m0, s36
	v_readfirstlane_b32 s36, v16
	v_add_u32_e32 v7, 0xc400, v7
	global_load_lds_dwordx4 v[14:15], off
	v_lshl_add_u64 v[14:15], v[8:9], 0, s[92:93]
	s_mov_b32 m0, s36
	v_readfirstlane_b32 s36, v7
	v_add_u32_e32 v2, 0x4000, v139
	global_load_lds_dwordx4 v[14:15], off
	s_mov_b32 m0, s36
	s_add_i32 s36, 16, 0xc000
	v_add_u32_e32 v7, s36, v2
	v_readlane_b32 s37, v235, 50
	v_lshl_add_u64 v[14:15], v[10:11], 0, s[92:93]
	v_readfirstlane_b32 s36, v7
	v_add_u32_e32 v7, s37, v138
	global_load_lds_dwordx4 v[14:15], off
	v_lshl_add_u64 v[14:15], v[12:13], 0, s[92:93]
	s_mov_b32 m0, s36
	v_readfirstlane_b32 s36, v7
	v_add_u32_e32 v7, 0x400, v7
	global_load_lds_dwordx4 v[14:15], off
	v_lshl_add_u64 v[8:9], v[8:9], 0, s[2:3]
	s_mov_b32 m0, s36
	v_readfirstlane_b32 s36, v7
	v_add_u32_e32 v2, s37, v2
	global_load_lds_dwordx4 v[8:9], off
	v_lshl_add_u64 v[8:9], v[10:11], 0, s[2:3]
	s_mov_b32 m0, s36
	v_readfirstlane_b32 s36, v2
	global_load_lds_dwordx4 v[8:9], off
	v_lshl_add_u64 v[8:9], v[12:13], 0, s[2:3]
	s_mov_b32 m0, s36
	v_readfirstlane_b32 s36, v137
	global_load_lds_dwordx4 v[8:9], off
	s_waitcnt vmcnt(6)
	s_and_b32 s37, s36, 0xffffff00
	s_cmpk_lg_i32 s37, 0x100
	s_barrier
	s_cbranch_scc1 .LBB0_78
	s_barrier
	s_setprio 1

.LBB0_86:
	s_setprio 0
	s_cmpk_lt_u32 s36, 0x100
	s_cbranch_scc0 .LBB0_71
	s_barrier
	s_branch .LBB0_71
.LBB0_88:
	v_mov_b32_e32 v92, v200
	v_readlane_b32 s24, v236, 7
	v_ashrrev_i32_e32 v2, 6, v92
	v_bfe_u32 v4, v92, 2, 4
	v_lshlrev_b32_e32 v5, 4, v2
	v_lshrrev_b32_e32 v0, 4, v92
	v_or_b32_e32 v6, v5, v4
	v_xor_b32_e32 v0, v0, v92
	v_ashrrev_i32_e32 v7, 31, v6
	v_lshlrev_b64 v[8:9], 13, v[6:7]
	v_lshlrev_b32_e32 v7, 4, v0
	v_add_u32_e32 v6, s73, v6
	v_readlane_b32 s25, v236, 8
	s_add_u32 s24, s46, s24
	v_and_b32_e32 v10, 48, v7
	v_ashrrev_i32_e32 v7, 31, v6
	s_addc_u32 s25, s47, s25
	v_lshlrev_b64 v[6:7], 13, v[6:7]
	v_and_b32_e32 v1, 63, v92
	v_lshl_add_u64 v[8:9], s[24:25], 0, v[8:9]
	v_mov_b32_e32 v11, v3
	v_lshl_add_u64 v[6:7], s[50:51], 0, v[6:7]
	v_lshl_add_u64 v[8:9], v[8:9], 0, v[10:11]
	v_lshl_add_u64 v[6:7], v[6:7], 0, v[10:11]
	v_lshlrev_b32_e32 v10, 4, v1
	v_lshl_or_b32 v93, v2, 10, v10
	s_mov_b64 s[24:25], 0xaa08000
	v_add_u32_e32 v2, 16, v93
	v_lshl_add_u64 v[12:13], v[8:9], 0, s[24:25]
	v_readfirstlane_b32 s24, v2
	v_add_u32_e32 v10, 0x2000, v2
	s_mov_b32 m0, s24
	v_readfirstlane_b32 s24, v10
	global_load_lds_dwordx4 v[12:13], off
	s_mov_b32 m0, s24
	s_mov_b64 s[24:25], 0xaa08040
	v_add_u32_e32 v12, 0x4000, v2
	v_lshl_add_u64 v[10:11], v[8:9], 0, s[24:25]
	v_readfirstlane_b32 s24, v12
	v_add_u32_e32 v12, 0x6000, v2
	global_load_lds_dwordx4 v[6:7], off
	s_mov_b32 m0, s24
	v_readfirstlane_b32 s24, v12
	global_load_lds_dwordx4 v[10:11], off
	v_lshl_add_u64 v[10:11], v[6:7], 0, 64
	s_mov_b32 m0, s24
	s_mov_b64 s[24:25], 0xaa08080
	v_add_u32_e32 v12, 0x8000, v2
	global_load_lds_dwordx4 v[10:11], off
	v_lshl_add_u64 v[10:11], v[8:9], 0, s[24:25]
	v_readfirstlane_b32 s24, v12
	v_add_u32_e32 v12, 0xa000, v2
	s_mov_b32 m0, s24
	v_readfirstlane_b32 s24, v12
	global_load_lds_dwordx4 v[10:11], off
	v_lshl_add_u64 v[10:11], v[6:7], 0, s[92:93]
	s_mov_b32 m0, s24
	s_mov_b64 s[24:25], 0xaa080c0
	global_load_lds_dwordx4 v[10:11], off
	v_add_u32_e32 v10, 0xc000, v2
	v_lshl_add_u64 v[8:9], v[8:9], 0, s[24:25]
	v_readfirstlane_b32 s24, v10
	v_add_u32_e32 v2, 0xe000, v2
	s_mov_b32 m0, s24
	v_readfirstlane_b32 s24, v2
	global_load_lds_dwordx4 v[8:9], off
	v_lshl_add_u64 v[6:7], v[6:7], 0, s[2:3]
	s_mov_b32 m0, s24
	v_readfirstlane_b32 s24, v92
	global_load_lds_dwordx4 v[6:7], off
	s_waitcnt vmcnt(4)
	s_and_b32 s25, s24, 0xffffff00
	s_cmpk_lg_i32 s25, 0x100
	s_barrier
	s_cbranch_scc1 .LBB0_90
	s_barrier
	s_setprio 1

.LBB0_104:
	s_setprio 0
	s_cmpk_lt_u32 s24, 0x100
	s_cbranch_scc0 .LBB0_106
	s_barrier

.LBB0_115:
	v_mov_b32_e32 v6, v200
	s_lshl_b32 s24, s25, 4
	s_sub_i32 s24, s56, s24
	v_ashrrev_i32_e32 v8, 6, v6
	v_bfe_u32 v4, v6, 2, 4
	v_lshlrev_b32_e32 v5, 5, v8
	v_and_b32_e32 v7, 63, v6
	v_or_b32_e32 v9, v5, v4
	s_lshl_b32 s30, s24, 8
	v_bfe_u32 v176, v200, 6, 2
	v_bfe_u32 v177, v200, 5, 1
	v_lshlrev_b32_e32 v176, 6, v176
	v_lshl_or_b32 v176, v177, 2, v176
	v_add_u32_e32 v176, s30, v176
	v_lshlrev_b32_e32 v176, 2, v176
	global_load_dwordx4 v[144:147], v176, s[54:55]
	global_load_dwordx4 v[148:151], v176, s[54:55] offset:32
	global_load_dwordx4 v[152:155], v176, s[54:55] offset:64
	global_load_dwordx4 v[156:159], v176, s[54:55] offset:96
	global_load_dwordx4 v[160:163], v176, s[54:55] offset:128
	global_load_dwordx4 v[164:167], v176, s[54:55] offset:160
	global_load_dwordx4 v[168:171], v176, s[54:55] offset:192
	global_load_dwordx4 v[172:175], v176, s[54:55] offset:224
	v_lshrrev_b32_e32 v2, 4, v6
	v_add_u32_e32 v10, s36, v9
	v_or_b32_e32 v16, 16, v9
	v_add_u32_e32 v14, s30, v9
	v_lshlrev_b32_e32 v9, 4, v7
	v_xor_b32_e32 v2, v2, v6
	v_ashrrev_i32_e32 v11, 31, v10
	v_add_u32_e32 v12, s36, v16
	v_lshl_or_b32 v185, v8, 11, v9
	v_lshlrev_b64 v[10:11], 11, v[10:11]
	v_lshlrev_b32_e32 v2, 4, v2
	v_ashrrev_i32_e32 v13, 31, v12
	v_add_u32_e32 v9, 16, v185
	v_lshl_add_u64 v[10:11], s[42:43], 0, v[10:11]
	v_and_b32_e32 v2, 48, v2
	v_lshlrev_b64 v[12:13], 11, v[12:13]
	v_ashrrev_i32_e32 v15, 31, v14
	v_add_u32_e32 v16, s30, v16
	v_readfirstlane_b32 s24, v9
	v_add_u32_e32 v18, 0x400, v9
	v_lshl_add_u64 v[10:11], v[10:11], 0, v[2:3]
	v_lshl_add_u64 v[12:13], s[42:43], 0, v[12:13]
	v_lshlrev_b64 v[14:15], 11, v[14:15]
	v_ashrrev_i32_e32 v17, 31, v16
	s_mov_b32 m0, s24
	v_readfirstlane_b32 s24, v18
	v_add_u32_e32 v18, 0x4000, v9
	v_lshl_add_u64 v[12:13], v[12:13], 0, v[2:3]
	v_lshl_add_u64 v[14:15], s[44:45], 0, v[14:15]
	v_lshlrev_b64 v[16:17], 11, v[16:17]
	global_load_lds_dwordx4 v[10:11], off
	s_mov_b32 m0, s24
	v_readfirstlane_b32 s24, v18
	v_add_u32_e32 v18, 0x4400, v9
	v_lshl_add_u64 v[14:15], v[14:15], 0, v[2:3]
	v_lshl_add_u64 v[16:17], s[44:45], 0, v[16:17]
	global_load_lds_dwordx4 v[12:13], off
	s_mov_b32 m0, s24
	v_readfirstlane_b32 s24, v18
	v_add_u32_e32 v20, 0x8000, v9
	v_lshl_add_u64 v[16:17], v[16:17], 0, v[2:3]
	global_load_lds_dwordx4 v[14:15], off
	s_mov_b32 m0, s24
	v_readfirstlane_b32 s24, v20
	v_add_u32_e32 v20, 0x8400, v9
	global_load_lds_dwordx4 v[16:17], off
	v_lshl_add_u64 v[18:19], v[10:11], 0, 64
	s_mov_b32 m0, s24
	v_readfirstlane_b32 s24, v20
	v_add_u32_e32 v20, 0xc000, v9
	global_load_lds_dwordx4 v[18:19], off
	v_lshl_add_u64 v[18:19], v[12:13], 0, 64
	s_mov_b32 m0, s24
	v_readfirstlane_b32 s24, v20
	v_add_u32_e32 v9, 0xc400, v9
	global_load_lds_dwordx4 v[18:19], off
	v_lshl_add_u64 v[18:19], v[14:15], 0, 64
	s_mov_b32 m0, s24
	v_readfirstlane_b32 s24, v9
	global_load_lds_dwordx4 v[18:19], off
	s_mov_b32 m0, s24
	s_add_i32 s24, 16, 0x10000
	v_add_u32_e32 v9, s24, v185
	v_lshl_add_u64 v[18:19], v[16:17], 0, 64
	v_readfirstlane_b32 s24, v9
	global_load_lds_dwordx4 v[18:19], off
	v_lshl_add_u64 v[10:11], v[10:11], 0, s[92:93]
	s_mov_b32 m0, s24
	s_nop 0
	global_load_lds_dwordx4 v[10:11], off
	v_lshl_add_u64 v[10:11], v[12:13], 0, s[92:93]
	v_add_u32_e32 v12, 0x400, v9
	s_nop 0
	v_readfirstlane_b32 s24, v12
	v_add_u32_e32 v12, 0x4000, v9
	s_mov_b32 m0, s24
	v_readfirstlane_b32 s24, v12
	v_add_u32_e32 v9, 0x4400, v9
	global_load_lds_dwordx4 v[10:11], off
	v_lshl_add_u64 v[10:11], v[14:15], 0, s[92:93]
	s_mov_b32 m0, s24
	v_readfirstlane_b32 s24, v9
	global_load_lds_dwordx4 v[10:11], off
	v_lshl_add_u64 v[10:11], v[16:17], 0, s[92:93]
	s_mov_b32 m0, s24
	v_readfirstlane_b32 s24, v6
	global_load_lds_dwordx4 v[10:11], off
	s_waitcnt vmcnt(8)
	s_and_b32 s31, s24, 0xffffff00
	s_cmpk_lg_i32 s31, 0x100
	s_barrier
	s_cbranch_scc1 .LBB0_117
	s_barrier
	s_setprio 1

.LBB0_125:
	s_setprio 0
	s_cmpk_lt_u32 s24, 0x100
	s_cbranch_scc0 .LBB0_110
	s_barrier
	s_branch .LBB0_110

.LBB0_164:
	s_ashr_i32 s25, s24, 31
	s_lshr_b32 s25, s25, 29
	v_mov_b32_e32 v137, v200
	s_add_i32 s25, s24, s25
	s_ashr_i32 s34, s25, 3
	v_ashrrev_i32_e32 v14, 6, v137
	s_and_b32 s25, s25, 0x1fffff8
	v_bfe_u32 v4, v137, 2, 4
	v_lshlrev_b32_e32 v5, 5, v14
	s_sub_i32 s30, s24, s25
	v_or_b32_e32 v2, v5, v4
	s_lshl_b32 s25, s34, 8
	v_add_u32_e32 v6, s25, v2
	v_ashrrev_i32_e32 v7, 31, v6
	v_lshrrev_b32_e32 v0, 4, v137
	v_lshlrev_b64 v[8:9], 11, v[6:7]
	v_or_b32_e32 v6, 16, v6
	v_xor_b32_e32 v0, v0, v137
	v_ashrrev_i32_e32 v7, 31, v6
	v_lshlrev_b32_e32 v2, 4, v0
	v_lshlrev_b64 v[6:7], 11, v[6:7]
	v_and_b32_e32 v2, 48, v2
	v_lshl_add_u64 v[6:7], s[50:51], 0, v[6:7]
	s_lshl_b32 s30, s30, 7
	v_lshl_add_u64 v[10:11], v[6:7], 0, v[2:3]
	v_lshlrev_b32_e32 v6, 4, v14
	v_or_b32_e32 v7, s30, v4
	v_add_u32_e32 v12, v7, v6
	v_ashrrev_i32_e32 v13, 31, v12
	v_lshlrev_b64 v[12:13], 11, v[12:13]
	v_and_b32_e32 v1, 63, v137
	v_lshl_add_u64 v[8:9], s[50:51], 0, v[8:9]
	v_lshl_add_u64 v[12:13], s[48:49], 0, v[12:13]
	v_lshl_add_u64 v[8:9], v[8:9], 0, v[2:3]
	v_lshl_add_u64 v[12:13], v[12:13], 0, v[2:3]
	v_lshlrev_b32_e32 v2, 4, v1
	v_lshl_or_b32 v138, v14, 11, v2
	v_lshl_or_b32 v139, v14, 10, v2
	v_add_u32_e32 v7, 16, v138
	v_add_u32_e32 v14, 0x400, v7
	v_readfirstlane_b32 s31, v7
	v_add_u32_e32 v16, 16, v139
	s_mov_b32 m0, s31
	v_readfirstlane_b32 s31, v14
	v_add_u32_e32 v14, 0x4000, v16
	global_load_lds_dwordx4 v[8:9], off
	s_mov_b32 m0, s31
	v_readfirstlane_b32 s31, v14
	v_add_u32_e32 v17, 0x6000, v7
	global_load_lds_dwordx4 v[10:11], off
	s_mov_b32 m0, s31
	v_readfirstlane_b32 s31, v17
	v_add_u32_e32 v17, 0x6400, v7
	global_load_lds_dwordx4 v[12:13], off
	v_lshl_add_u64 v[14:15], v[8:9], 0, 64
	s_mov_b32 m0, s31
	v_readfirstlane_b32 s31, v17
	v_add_u32_e32 v16, 0xa000, v16
	global_load_lds_dwordx4 v[14:15], off
	v_lshl_add_u64 v[14:15], v[10:11], 0, 64
	s_mov_b32 m0, s31
	v_readfirstlane_b32 s31, v16
	v_add_u32_e32 v16, 0xc000, v7
	global_load_lds_dwordx4 v[14:15], off
	v_lshl_add_u64 v[14:15], v[12:13], 0, 64
	s_mov_b32 m0, s31
	v_readfirstlane_b32 s31, v16
	v_add_u32_e32 v7, 0xc400, v7
	global_load_lds_dwordx4 v[14:15], off
	v_lshl_add_u64 v[14:15], v[8:9], 0, s[92:93]
	s_mov_b32 m0, s31
	v_readfirstlane_b32 s31, v7
	v_add_u32_e32 v2, 0x4000, v139
	global_load_lds_dwordx4 v[14:15], off
	s_mov_b32 m0, s31
	s_add_i32 s31, 16, 0xc000
	v_add_u32_e32 v7, s31, v2
	v_readlane_b32 s35, v235, 50
	v_lshl_add_u64 v[14:15], v[10:11], 0, s[92:93]
	v_readfirstlane_b32 s31, v7
	v_add_u32_e32 v7, s35, v138
	global_load_lds_dwordx4 v[14:15], off
	v_lshl_add_u64 v[14:15], v[12:13], 0, s[92:93]
	s_mov_b32 m0, s31
	v_readfirstlane_b32 s31, v7
	v_add_u32_e32 v7, 0x400, v7
	global_load_lds_dwordx4 v[14:15], off
	v_lshl_add_u64 v[8:9], v[8:9], 0, s[2:3]
	s_mov_b32 m0, s31
	v_readfirstlane_b32 s31, v7
	v_add_u32_e32 v2, s35, v2
	global_load_lds_dwordx4 v[8:9], off
	v_lshl_add_u64 v[8:9], v[10:11], 0, s[2:3]
	s_mov_b32 m0, s31
	v_readfirstlane_b32 s31, v2
	global_load_lds_dwordx4 v[8:9], off
	v_lshl_add_u64 v[8:9], v[12:13], 0, s[2:3]
	s_mov_b32 m0, s31
	v_readfirstlane_b32 s31, v137
	global_load_lds_dwordx4 v[8:9], off
	s_waitcnt vmcnt(6)
	s_and_b32 s35, s31, 0xffffff00
	s_cmpk_lg_i32 s35, 0x100
	s_barrier
	s_cbranch_scc1 .LBB0_166
	s_barrier
	s_setprio 1

.LBB0_174:
	s_setprio 0
	s_cmpk_lt_u32 s31, 0x100
	s_cbranch_scc0 .LBB0_163
	s_barrier
	s_branch .LBB0_163

.LBB0_182:
	v_mov_b32_e32 v137, v200
	s_and_b32 s28, s34, 56
	s_or_b32 s28, s28, s83
	v_ashrrev_i32_e32 v14, 6, v137
	v_bfe_u32 v4, v137, 2, 4
	v_lshlrev_b32_e32 v5, 5, v14
	v_or_b32_e32 v2, v5, v4
	s_lshl_b32 s36, s28, 8
	v_add_u32_e32 v6, s36, v2
	v_ashrrev_i32_e32 v7, 31, v6
	v_lshrrev_b32_e32 v0, 4, v137
	v_lshlrev_b64 v[8:9], 11, v[6:7]
	v_or_b32_e32 v6, 16, v6
	v_xor_b32_e32 v0, v0, v137
	v_ashrrev_i32_e32 v7, 31, v6
	v_lshlrev_b32_e32 v2, 4, v0
	v_lshlrev_b64 v[6:7], 11, v[6:7]
	s_lshl_b32 s28, s34, 7
	v_and_b32_e32 v2, 48, v2
	v_lshl_add_u64 v[6:7], s[50:51], 0, v[6:7]
	s_and_b32 s35, s28, 0x380
	v_lshl_add_u64 v[10:11], v[6:7], 0, v[2:3]
	v_lshlrev_b32_e32 v6, 4, v14
	v_or_b32_e32 v7, s35, v4
	v_add_u32_e32 v12, v7, v6
	v_ashrrev_i32_e32 v13, 31, v12
	v_lshlrev_b64 v[12:13], 11, v[12:13]
	v_and_b32_e32 v1, 63, v137
	v_lshl_add_u64 v[8:9], s[50:51], 0, v[8:9]
	v_lshl_add_u64 v[12:13], s[48:49], 0, v[12:13]
	v_lshl_add_u64 v[8:9], v[8:9], 0, v[2:3]
	v_lshl_add_u64 v[12:13], v[12:13], 0, v[2:3]
	v_lshlrev_b32_e32 v2, 4, v1
	v_lshl_or_b32 v138, v14, 11, v2
	v_lshl_or_b32 v139, v14, 10, v2
	v_add_u32_e32 v7, 16, v138
	v_add_u32_e32 v14, 0x400, v7
	v_readfirstlane_b32 s28, v7
	v_add_u32_e32 v16, 16, v139
	s_mov_b32 m0, s28
	v_readfirstlane_b32 s28, v14
	v_add_u32_e32 v14, 0x4000, v16
	global_load_lds_dwordx4 v[8:9], off
	s_mov_b32 m0, s28
	v_readfirstlane_b32 s28, v14
	v_add_u32_e32 v17, 0x6000, v7
	global_load_lds_dwordx4 v[10:11], off
	s_mov_b32 m0, s28
	v_readfirstlane_b32 s28, v17
	v_add_u32_e32 v17, 0x6400, v7
	global_load_lds_dwordx4 v[12:13], off
	v_lshl_add_u64 v[14:15], v[8:9], 0, 64
	s_mov_b32 m0, s28
	v_readfirstlane_b32 s28, v17
	v_add_u32_e32 v16, 0xa000, v16
	global_load_lds_dwordx4 v[14:15], off
	v_lshl_add_u64 v[14:15], v[10:11], 0, 64
	s_mov_b32 m0, s28
	v_readfirstlane_b32 s28, v16
	v_add_u32_e32 v16, 0xc000, v7
	global_load_lds_dwordx4 v[14:15], off
	v_lshl_add_u64 v[14:15], v[12:13], 0, 64
	s_mov_b32 m0, s28
	v_readfirstlane_b32 s28, v16
	v_add_u32_e32 v7, 0xc400, v7
	global_load_lds_dwordx4 v[14:15], off
	v_lshl_add_u64 v[14:15], v[8:9], 0, s[92:93]
	s_mov_b32 m0, s28
	v_readfirstlane_b32 s28, v7
	v_add_u32_e32 v2, 0x4000, v139
	global_load_lds_dwordx4 v[14:15], off
	s_mov_b32 m0, s28
	s_add_i32 s28, 16, 0xc000
	v_add_u32_e32 v7, s28, v2
	v_readlane_b32 s29, v235, 50
	v_lshl_add_u64 v[14:15], v[10:11], 0, s[92:93]
	v_readfirstlane_b32 s28, v7
	v_add_u32_e32 v7, s29, v138
	global_load_lds_dwordx4 v[14:15], off
	v_lshl_add_u64 v[14:15], v[12:13], 0, s[92:93]
	s_mov_b32 m0, s28
	v_readfirstlane_b32 s28, v7
	v_add_u32_e32 v7, 0x400, v7
	global_load_lds_dwordx4 v[14:15], off
	v_lshl_add_u64 v[8:9], v[8:9], 0, s[2:3]
	s_mov_b32 m0, s28
	v_readfirstlane_b32 s28, v7
	v_add_u32_e32 v2, s29, v2
	global_load_lds_dwordx4 v[8:9], off
	v_lshl_add_u64 v[8:9], v[10:11], 0, s[2:3]
	s_mov_b32 m0, s28
	v_readfirstlane_b32 s28, v2
	global_load_lds_dwordx4 v[8:9], off
	v_lshl_add_u64 v[8:9], v[12:13], 0, s[2:3]
	s_mov_b32 m0, s28
	v_readfirstlane_b32 s37, v137
	global_load_lds_dwordx4 v[8:9], off
	s_waitcnt vmcnt(6)
	s_and_b32 s28, s37, 0xffffff00
	s_cmpk_lg_i32 s28, 0x100
	s_barrier
	s_cbranch_scc1 .LBB0_184
	s_barrier
	s_setprio 1

.LBB0_192:
	s_setprio 0
	s_cmpk_lt_u32 s37, 0x100
	s_cbranch_scc0 .LBB0_181
	s_barrier
	s_branch .LBB0_181

.LBB0_306:
	s_mul_hi_i32 s24, s82, 0x2aaaaaab
	s_lshr_b32 s25, s24, 31
	s_ashr_i32 s24, s24, 1
	s_add_i32 s28, s24, s25
	s_lshl_b32 s24, s28, 3
	s_or_b32 s29, s24, s83
	v_readlane_b32 s24, v236, 15
	v_readlane_b32 s25, v236, 16
	s_and_b64 s[24:25], s[24:25], exec
	s_cselect_b32 s24, s28, s29
	s_mul_i32 s28, s28, 12
	s_mul_i32 s35, s24, 12
	s_sub_i32 s24, s82, s28
	s_add_i32 s35, s35, s24
	s_mul_hi_i32 s24, s35, 0x2aaaaaab
	s_lshr_b32 s25, s24, 31
	s_ashr_i32 s24, s24, 1
	s_add_i32 s34, s24, s25
	s_mul_i32 s24, s34, 12
	s_sub_i32 s48, s35, s24
	s_lshl_b32 s83, s34, 8
	s_cmp_gt_i32 s48, 7
	s_mov_b64 s[28:29], -1
	s_mulk_i32 s34, 0xc00
	s_cbranch_scc0 .LBB0_448
	v_mov_b32_e32 v0, v200
	s_lshl_b32 s24, s48, 8
	v_ashrrev_i32_e32 v6, 6, v0
	v_bfe_u32 v5, v0, 2, 4
	v_lshlrev_b32_e32 v4, 5, v6
	v_and_b32_e32 v1, 63, v0
	v_or_b32_e32 v7, v4, v5
	v_lshrrev_b32_e32 v2, 4, v0
	v_add_u32_e32 v8, s83, v7
	v_or_b32_e32 v14, 16, v7
	v_add_u32_e32 v12, s24, v7
	v_lshlrev_b32_e32 v7, 4, v1
	v_xor_b32_e32 v2, v2, v0
	v_ashrrev_i32_e32 v9, 31, v8
	v_add_u32_e32 v10, s83, v14
	v_lshl_or_b32 v189, v6, 11, v7
	v_lshlrev_b64 v[8:9], 11, v[8:9]
	v_lshlrev_b32_e32 v2, 4, v2
	v_ashrrev_i32_e32 v11, 31, v10
	v_add_u32_e32 v7, 16, v189
	v_lshl_add_u64 v[8:9], s[62:63], 0, v[8:9]
	v_and_b32_e32 v2, 48, v2
	v_lshlrev_b64 v[10:11], 11, v[10:11]
	v_ashrrev_i32_e32 v13, 31, v12
	v_add_u32_e32 v14, s24, v14
	v_readfirstlane_b32 s25, v7
	v_add_u32_e32 v16, 0x400, v7
	v_lshl_add_u64 v[8:9], v[8:9], 0, v[2:3]
	v_lshl_add_u64 v[10:11], s[62:63], 0, v[10:11]
	v_lshlrev_b64 v[12:13], 11, v[12:13]
	v_ashrrev_i32_e32 v15, 31, v14
	s_mov_b32 m0, s25
	v_readfirstlane_b32 s25, v16
	v_add_u32_e32 v16, 0x4000, v7
	v_lshl_add_u64 v[10:11], v[10:11], 0, v[2:3]
	v_lshl_add_u64 v[12:13], s[64:65], 0, v[12:13]
	v_lshlrev_b64 v[14:15], 11, v[14:15]
	global_load_lds_dwordx4 v[8:9], off
	s_mov_b32 m0, s25
	v_readfirstlane_b32 s25, v16
	v_add_u32_e32 v16, 0x4400, v7
	v_lshl_add_u64 v[12:13], v[12:13], 0, v[2:3]
	v_lshl_add_u64 v[14:15], s[64:65], 0, v[14:15]
	global_load_lds_dwordx4 v[10:11], off
	s_mov_b32 m0, s25
	v_readfirstlane_b32 s25, v16
	v_add_u32_e32 v18, 0x8000, v7
	v_lshl_add_u64 v[14:15], v[14:15], 0, v[2:3]
	global_load_lds_dwordx4 v[12:13], off
	s_mov_b32 m0, s25
	v_readfirstlane_b32 s25, v18
	v_add_u32_e32 v18, 0x8400, v7
	global_load_lds_dwordx4 v[14:15], off
	v_lshl_add_u64 v[16:17], v[8:9], 0, 64
	s_mov_b32 m0, s25
	v_readfirstlane_b32 s25, v18
	v_add_u32_e32 v18, 0xc000, v7
	global_load_lds_dwordx4 v[16:17], off
	v_lshl_add_u64 v[16:17], v[10:11], 0, 64
	s_mov_b32 m0, s25
	v_readfirstlane_b32 s25, v18
	v_add_u32_e32 v7, 0xc400, v7
	global_load_lds_dwordx4 v[16:17], off
	v_lshl_add_u64 v[16:17], v[12:13], 0, 64
	s_mov_b32 m0, s25
	v_readfirstlane_b32 s25, v7
	global_load_lds_dwordx4 v[16:17], off
	s_mov_b32 m0, s25
	s_add_i32 s25, 16, 0x10000
	v_add_u32_e32 v7, s25, v189
	v_lshl_add_u64 v[16:17], v[14:15], 0, 64
	v_readfirstlane_b32 s25, v7
	global_load_lds_dwordx4 v[16:17], off
	v_lshl_add_u64 v[8:9], v[8:9], 0, s[92:93]
	s_mov_b32 m0, s25
	s_nop 0
	global_load_lds_dwordx4 v[8:9], off
	v_lshl_add_u64 v[8:9], v[10:11], 0, s[92:93]
	v_add_u32_e32 v10, 0x400, v7
	s_nop 0
	v_readfirstlane_b32 s25, v10
	v_add_u32_e32 v10, 0x4000, v7
	s_mov_b32 m0, s25
	v_readfirstlane_b32 s25, v10
	v_add_u32_e32 v7, 0x4400, v7
	global_load_lds_dwordx4 v[8:9], off
	v_lshl_add_u64 v[8:9], v[12:13], 0, s[92:93]
	s_mov_b32 m0, s25
	v_readfirstlane_b32 s25, v7
	global_load_lds_dwordx4 v[8:9], off
	v_lshl_add_u64 v[8:9], v[14:15], 0, s[92:93]
	s_mov_b32 m0, s25
	v_readfirstlane_b32 s25, v0
	global_load_lds_dwordx4 v[8:9], off
	s_waitcnt vmcnt(8)
	s_and_b32 s28, s25, 0xffffff00
	s_cmpk_lg_i32 s28, 0x100
	s_barrier
	s_cbranch_scc1 .LBB0_309
	s_barrier
	s_setprio 1

.LBB0_317:
	s_setprio 0
	s_cmpk_lt_u32 s25, 0x100
	s_cbranch_scc0 .LBB0_319
	s_barrier

.LBB0_448:
	s_and_b64 vcc, exec, s[28:29]
	s_cbranch_vccz .LBB0_305
	v_mov_b32_e32 v0, v200
	s_lshl_b32 s30, s48, 8
	s_load_dwordx2 s[42:43], s[22:23], 0xe8
	s_waitcnt lgkmcnt(0)
	v_bfe_u32 v176, v200, 6, 2
	v_bfe_u32 v177, v200, 5, 1
	v_lshlrev_b32_e32 v176, 6, v176
	v_lshl_or_b32 v176, v177, 2, v176
	v_add_u32_e32 v176, s30, v176
	v_lshlrev_b32_e32 v176, 2, v176
	global_load_dwordx4 v[144:147], v176, s[42:43]
	global_load_dwordx4 v[148:151], v176, s[42:43] offset:32
	global_load_dwordx4 v[152:155], v176, s[42:43] offset:64
	global_load_dwordx4 v[156:159], v176, s[42:43] offset:96
	global_load_dwordx4 v[160:163], v176, s[42:43] offset:128
	global_load_dwordx4 v[164:167], v176, s[42:43] offset:160
	global_load_dwordx4 v[168:171], v176, s[42:43] offset:192
	global_load_dwordx4 v[172:175], v176, s[42:43] offset:224
	v_ashrrev_i32_e32 v7, 6, v0
	v_lshrrev_b32_e32 v1, 4, v0
	v_bfe_u32 v5, v0, 2, 4
	v_xor_b32_e32 v1, v1, v0
	v_lshlrev_b32_e32 v4, 5, v7
	v_or_b32_e32 v12, v4, v5
	v_lshlrev_b32_e32 v1, 4, v1
	v_and_b32_e32 v6, 63, v0
	v_and_b32_e32 v2, 48, v1
	v_or_b32_e32 v1, 16, v12
	v_add_u32_e32 v8, s83, v12
	v_add_u32_e32 v10, s83, v1
	v_add_u32_e32 v14, s30, v1
	v_lshlrev_b32_e32 v1, 4, v6
	v_ashrrev_i32_e32 v9, 31, v8
	v_lshl_or_b32 v1, v7, 11, v1
	v_lshlrev_b64 v[8:9], 11, v[8:9]
	v_ashrrev_i32_e32 v11, 31, v10
	v_add_u32_e32 v12, s30, v12
	v_add_u32_e32 v18, 16, v1
	v_lshl_add_u64 v[8:9], s[62:63], 0, v[8:9]
	v_lshlrev_b64 v[10:11], 11, v[10:11]
	v_ashrrev_i32_e32 v13, 31, v12
	v_readfirstlane_b32 s24, v18
	v_add_u32_e32 v16, 0x400, v18
	v_lshl_add_u64 v[8:9], v[8:9], 0, v[2:3]
	v_lshl_add_u64 v[10:11], s[62:63], 0, v[10:11]
	v_lshlrev_b64 v[12:13], 11, v[12:13]
	v_ashrrev_i32_e32 v15, 31, v14
	s_mov_b32 m0, s24
	v_readfirstlane_b32 s24, v16
	v_add_u32_e32 v16, 0x4000, v18
	v_lshl_add_u64 v[10:11], v[10:11], 0, v[2:3]
	v_lshl_add_u64 v[12:13], s[64:65], 0, v[12:13]
	v_lshlrev_b64 v[14:15], 11, v[14:15]
	global_load_lds_dwordx4 v[8:9], off
	s_mov_b32 m0, s24
	v_readfirstlane_b32 s24, v16
	v_add_u32_e32 v16, 0x4400, v18
	v_lshl_add_u64 v[12:13], v[12:13], 0, v[2:3]
	v_lshl_add_u64 v[14:15], s[64:65], 0, v[14:15]
	global_load_lds_dwordx4 v[10:11], off
	s_mov_b32 m0, s24
	v_readfirstlane_b32 s24, v16
	v_add_u32_e32 v19, 0x8000, v18
	v_lshl_add_u64 v[14:15], v[14:15], 0, v[2:3]
	global_load_lds_dwordx4 v[12:13], off
	s_mov_b32 m0, s24
	v_readfirstlane_b32 s24, v19
	v_add_u32_e32 v19, 0x8400, v18
	global_load_lds_dwordx4 v[14:15], off
	v_lshl_add_u64 v[16:17], v[8:9], 0, 64
	s_mov_b32 m0, s24
	v_readfirstlane_b32 s24, v19
	v_add_u32_e32 v19, 0xc000, v18
	global_load_lds_dwordx4 v[16:17], off
	v_lshl_add_u64 v[16:17], v[10:11], 0, 64
	s_mov_b32 m0, s24
	v_readfirstlane_b32 s24, v19
	v_add_u32_e32 v18, 0xc400, v18
	global_load_lds_dwordx4 v[16:17], off
	v_lshl_add_u64 v[16:17], v[12:13], 0, 64
	s_mov_b32 m0, s24
	v_readfirstlane_b32 s24, v18
	global_load_lds_dwordx4 v[16:17], off
	v_lshl_add_u64 v[16:17], v[14:15], 0, 64
	s_mov_b32 m0, s24
	s_add_i32 s24, 16, 0x10000
	global_load_lds_dwordx4 v[16:17], off
	v_add_u32_e32 v16, s24, v1
	v_lshl_add_u64 v[8:9], v[8:9], 0, s[92:93]
	v_readfirstlane_b32 s24, v16
	s_mov_b32 m0, s24
	s_nop 0
	global_load_lds_dwordx4 v[8:9], off
	v_lshl_add_u64 v[8:9], v[10:11], 0, s[92:93]
	v_add_u32_e32 v10, 0x400, v16
	s_nop 0
	v_readfirstlane_b32 s24, v10
	v_add_u32_e32 v10, 0x4000, v16
	s_mov_b32 m0, s24
	v_readfirstlane_b32 s24, v10
	v_add_u32_e32 v10, 0x4400, v16
	global_load_lds_dwordx4 v[8:9], off
	v_lshl_add_u64 v[8:9], v[12:13], 0, s[92:93]
	s_mov_b32 m0, s24
	v_readfirstlane_b32 s24, v10
	global_load_lds_dwordx4 v[8:9], off
	v_lshl_add_u64 v[8:9], v[14:15], 0, s[92:93]
	s_mov_b32 m0, s24
	v_readfirstlane_b32 s24, v0
	global_load_lds_dwordx4 v[8:9], off
	s_waitcnt vmcnt(8)
	s_and_b32 s25, s24, 0xffffff00
	s_cmpk_lg_i32 s25, 0x100
	s_barrier
	s_cbranch_scc1 .LBB0_451
	s_barrier
	s_setprio 1

.LBB0_704:
	v_mov_b32_e32 v137, v200
	s_lshl_b32 s25, s52, 3
	v_ashrrev_i32_e32 v14, 6, v137
	v_bfe_u32 v4, v137, 2, 4
	v_lshlrev_b32_e32 v5, 5, v14
	v_or_b32_e32 v6, v5, v4
	v_ashrrev_i32_e32 v7, 31, v6
	s_sub_i32 s25, s24, s25
	s_lshl_b64 s[50:51], s[30:31], 13
	v_lshrrev_b32_e32 v0, 4, v137
	v_lshlrev_b64 v[8:9], 13, v[6:7]
	v_or_b32_e32 v6, 16, v6
	s_waitcnt lgkmcnt(0)
	s_add_u32 s30, s36, s50
	v_xor_b32_e32 v0, v0, v137
	v_ashrrev_i32_e32 v7, 31, v6
	s_addc_u32 s31, s37, s51
	v_lshlrev_b32_e32 v2, 4, v0
	v_lshlrev_b64 v[6:7], 13, v[6:7]
	v_lshl_add_u64 v[8:9], s[30:31], 0, v[8:9]
	v_and_b32_e32 v2, 48, v2
	v_lshl_add_u64 v[6:7], s[30:31], 0, v[6:7]
	s_lshl_b32 s30, s25, 7
	v_lshl_add_u64 v[10:11], v[6:7], 0, v[2:3]
	v_lshlrev_b32_e32 v6, 4, v14
	v_or_b32_e32 v7, s30, v4
	v_add_u32_e32 v12, v7, v6
	v_ashrrev_i32_e32 v13, 31, v12
	v_lshlrev_b64 v[12:13], 13, v[12:13]
	v_and_b32_e32 v1, 63, v137
	v_lshl_add_u64 v[12:13], s[48:49], 0, v[12:13]
	v_lshl_add_u64 v[8:9], v[8:9], 0, v[2:3]
	v_lshl_add_u64 v[12:13], v[12:13], 0, v[2:3]
	v_lshlrev_b32_e32 v2, 4, v1
	v_lshl_or_b32 v138, v14, 11, v2
	v_lshl_or_b32 v139, v14, 10, v2
	v_add_u32_e32 v7, 16, v138
	v_add_u32_e32 v14, 0x400, v7
	v_readfirstlane_b32 s25, v7
	v_add_u32_e32 v16, 16, v139
	s_mov_b32 m0, s25
	v_readfirstlane_b32 s25, v14
	v_add_u32_e32 v14, 0x4000, v16
	global_load_lds_dwordx4 v[8:9], off
	s_mov_b32 m0, s25
	v_readfirstlane_b32 s25, v14
	v_add_u32_e32 v17, 0x6000, v7
	global_load_lds_dwordx4 v[10:11], off
	s_mov_b32 m0, s25
	v_readfirstlane_b32 s25, v17
	v_add_u32_e32 v17, 0x6400, v7
	global_load_lds_dwordx4 v[12:13], off
	v_lshl_add_u64 v[14:15], v[8:9], 0, 64
	s_mov_b32 m0, s25
	v_readfirstlane_b32 s25, v17
	v_add_u32_e32 v16, 0xa000, v16
	global_load_lds_dwordx4 v[14:15], off
	v_lshl_add_u64 v[14:15], v[10:11], 0, 64
	s_mov_b32 m0, s25
	v_readfirstlane_b32 s25, v16
	v_add_u32_e32 v16, 0xc000, v7
	global_load_lds_dwordx4 v[14:15], off
	v_lshl_add_u64 v[14:15], v[12:13], 0, 64
	s_mov_b32 m0, s25
	v_readfirstlane_b32 s25, v16
	v_add_u32_e32 v7, 0xc400, v7
	global_load_lds_dwordx4 v[14:15], off
	v_lshl_add_u64 v[14:15], v[8:9], 0, s[92:93]
	s_mov_b32 m0, s25
	v_readfirstlane_b32 s25, v7
	v_add_u32_e32 v2, 0x4000, v139
	global_load_lds_dwordx4 v[14:15], off
	s_mov_b32 m0, s25
	s_add_i32 s25, 16, 0xc000
	v_add_u32_e32 v7, s25, v2
	v_readlane_b32 s31, v235, 50
	v_lshl_add_u64 v[14:15], v[10:11], 0, s[92:93]
	v_readfirstlane_b32 s25, v7
	v_add_u32_e32 v7, s31, v138
	global_load_lds_dwordx4 v[14:15], off
	v_lshl_add_u64 v[14:15], v[12:13], 0, s[92:93]
	s_mov_b32 m0, s25
	v_readfirstlane_b32 s25, v7
	v_add_u32_e32 v7, 0x400, v7
	global_load_lds_dwordx4 v[14:15], off
	v_lshl_add_u64 v[8:9], v[8:9], 0, s[2:3]
	s_mov_b32 m0, s25
	v_readfirstlane_b32 s25, v7
	v_add_u32_e32 v2, s31, v2
	global_load_lds_dwordx4 v[8:9], off
	v_lshl_add_u64 v[8:9], v[10:11], 0, s[2:3]
	s_mov_b32 m0, s25
	v_readfirstlane_b32 s25, v2
	global_load_lds_dwordx4 v[8:9], off
	v_lshl_add_u64 v[8:9], v[12:13], 0, s[2:3]
	s_mov_b32 m0, s25
	v_readfirstlane_b32 s25, v137
	global_load_lds_dwordx4 v[8:9], off
	s_waitcnt vmcnt(6)
	s_and_b32 s31, s25, 0xffffff00
	s_cmpk_lg_i32 s31, 0x100
	s_barrier
	s_cbranch_scc1 .LBB0_706
	s_barrier
	s_setprio 1

.LBB0_729:
	v_mov_b32_e32 v0, v200
	s_lshl_b32 s30, s52, 4
	v_ashrrev_i32_e32 v7, 6, v0
	v_lshrrev_b32_e32 v1, 4, v0
	v_bfe_u32 v4, v0, 2, 4
	v_xor_b32_e32 v1, v1, v0
	v_lshlrev_b32_e32 v5, 5, v7
	s_sub_i32 s30, s54, s30
	v_or_b32_e32 v12, v5, v4
	v_lshlrev_b32_e32 v1, 4, v1
	v_and_b32_e32 v6, 63, v0
	v_and_b32_e32 v2, 48, v1
	v_or_b32_e32 v1, 16, v12
	s_lshl_b32 s30, s30, 8
	v_bfe_u32 v176, v200, 6, 2
	v_bfe_u32 v177, v200, 5, 1
	v_lshlrev_b32_e32 v176, 6, v176
	v_lshl_or_b32 v176, v177, 2, v176
	v_add_u32_e32 v176, s30, v176
	v_lshlrev_b32_e32 v176, 2, v176
	global_load_dwordx4 v[144:147], v176, s[24:25]
	global_load_dwordx4 v[148:151], v176, s[24:25] offset:32
	global_load_dwordx4 v[152:155], v176, s[24:25] offset:64
	global_load_dwordx4 v[156:159], v176, s[24:25] offset:96
	global_load_dwordx4 v[160:163], v176, s[24:25] offset:128
	global_load_dwordx4 v[164:167], v176, s[24:25] offset:160
	global_load_dwordx4 v[168:171], v176, s[24:25] offset:192
	global_load_dwordx4 v[172:175], v176, s[24:25] offset:224
	v_add_u32_e32 v8, s36, v12
	v_add_u32_e32 v10, s36, v1
	v_add_u32_e32 v14, s30, v1
	v_lshlrev_b32_e32 v1, 4, v6
	v_ashrrev_i32_e32 v9, 31, v8
	v_lshl_or_b32 v1, v7, 11, v1
	v_lshlrev_b64 v[8:9], 11, v[8:9]
	v_ashrrev_i32_e32 v11, 31, v10
	v_add_u32_e32 v12, s30, v12
	v_add_u32_e32 v18, 16, v1
	v_lshl_add_u64 v[8:9], s[42:43], 0, v[8:9]
	v_lshlrev_b64 v[10:11], 11, v[10:11]
	v_ashrrev_i32_e32 v13, 31, v12
	v_readfirstlane_b32 s31, v18
	v_add_u32_e32 v16, 0x400, v18
	v_lshl_add_u64 v[8:9], v[8:9], 0, v[2:3]
	v_lshl_add_u64 v[10:11], s[42:43], 0, v[10:11]
	v_lshlrev_b64 v[12:13], 11, v[12:13]
	v_ashrrev_i32_e32 v15, 31, v14
	s_mov_b32 m0, s31
	v_readfirstlane_b32 s31, v16
	v_add_u32_e32 v16, 0x4000, v18
	v_lshl_add_u64 v[10:11], v[10:11], 0, v[2:3]
	v_lshl_add_u64 v[12:13], s[44:45], 0, v[12:13]
	v_lshlrev_b64 v[14:15], 11, v[14:15]
	global_load_lds_dwordx4 v[8:9], off
	s_mov_b32 m0, s31
	v_readfirstlane_b32 s31, v16
	v_add_u32_e32 v16, 0x4400, v18
	v_lshl_add_u64 v[12:13], v[12:13], 0, v[2:3]
	v_lshl_add_u64 v[14:15], s[44:45], 0, v[14:15]
	global_load_lds_dwordx4 v[10:11], off
	s_mov_b32 m0, s31
	v_readfirstlane_b32 s31, v16
	v_add_u32_e32 v19, 0x8000, v18
	v_lshl_add_u64 v[14:15], v[14:15], 0, v[2:3]
	global_load_lds_dwordx4 v[12:13], off
	s_mov_b32 m0, s31
	v_readfirstlane_b32 s31, v19
	v_add_u32_e32 v19, 0x8400, v18
	global_load_lds_dwordx4 v[14:15], off
	v_lshl_add_u64 v[16:17], v[8:9], 0, 64
	s_mov_b32 m0, s31
	v_readfirstlane_b32 s31, v19
	v_add_u32_e32 v19, 0xc000, v18
	global_load_lds_dwordx4 v[16:17], off
	v_lshl_add_u64 v[16:17], v[10:11], 0, 64
	s_mov_b32 m0, s31
	v_readfirstlane_b32 s31, v19
	v_add_u32_e32 v18, 0xc400, v18
	global_load_lds_dwordx4 v[16:17], off
	v_lshl_add_u64 v[16:17], v[12:13], 0, 64
	s_mov_b32 m0, s31
	v_readfirstlane_b32 s31, v18
	global_load_lds_dwordx4 v[16:17], off
	v_lshl_add_u64 v[16:17], v[14:15], 0, 64
	s_mov_b32 m0, s31
	s_add_i32 s31, 16, 0x10000
	global_load_lds_dwordx4 v[16:17], off
	v_add_u32_e32 v16, s31, v1
	v_lshl_add_u64 v[8:9], v[8:9], 0, s[92:93]
	v_readfirstlane_b32 s31, v16
	s_mov_b32 m0, s31
	s_nop 0
	global_load_lds_dwordx4 v[8:9], off
	v_lshl_add_u64 v[8:9], v[10:11], 0, s[92:93]
	v_add_u32_e32 v10, 0x400, v16
	s_nop 0
	v_readfirstlane_b32 s31, v10
	v_add_u32_e32 v10, 0x4000, v16
	s_mov_b32 m0, s31
	v_readfirstlane_b32 s31, v10
	v_add_u32_e32 v10, 0x4400, v16
	global_load_lds_dwordx4 v[8:9], off
	v_lshl_add_u64 v[8:9], v[12:13], 0, s[92:93]
	s_mov_b32 m0, s31
	v_readfirstlane_b32 s31, v10
	global_load_lds_dwordx4 v[8:9], off
	v_lshl_add_u64 v[8:9], v[14:15], 0, s[92:93]
	s_mov_b32 m0, s31
	v_readfirstlane_b32 s31, v0
	global_load_lds_dwordx4 v[8:9], off
	s_waitcnt vmcnt(8)
	s_and_b32 s37, s31, 0xffffff00
	s_cmpk_lg_i32 s37, 0x100
	s_barrier
	s_cbranch_scc1 .LBB0_731
	s_barrier
	s_setprio 1

.LBB0_743:
	v_mov_b32_e32 v92, v200
	v_readlane_b32 s24, v236, 6
	v_ashrrev_i32_e32 v2, 6, v92
	v_bfe_u32 v4, v92, 2, 4
	v_lshlrev_b32_e32 v5, 4, v2
	v_or_b32_e32 v10, v5, v4
	v_lshrrev_b32_e32 v0, 4, v92
	v_add_u32_e32 v6, s24, v10
	v_add_u32_e32 v10, s73, v10
	v_xor_b32_e32 v0, v0, v92
	v_ashrrev_i32_e32 v7, 31, v6
	v_ashrrev_i32_e32 v11, 31, v10
	v_lshlrev_b64 v[6:7], 11, v[6:7]
	v_lshlrev_b32_e32 v8, 4, v0
	v_lshlrev_b64 v[10:11], 11, v[10:11]
	v_and_b32_e32 v1, 63, v92
	v_lshl_add_u64 v[6:7], s[50:51], 0, v[6:7]
	v_and_b32_e32 v8, 48, v8
	v_mov_b32_e32 v9, v3
	v_lshl_add_u64 v[10:11], s[48:49], 0, v[10:11]
	v_lshl_add_u64 v[6:7], v[6:7], 0, v[8:9]
	v_lshl_add_u64 v[8:9], v[10:11], 0, v[8:9]
	v_lshlrev_b32_e32 v10, 4, v1
	v_lshl_or_b32 v93, v2, 10, v10
	v_add_u32_e32 v2, 16, v93
	v_add_u32_e32 v10, 0x2000, v2
	v_readfirstlane_b32 s24, v2
	s_mov_b32 m0, s24
	v_readfirstlane_b32 s24, v10
	v_add_u32_e32 v12, 0x4000, v2
	global_load_lds_dwordx4 v[6:7], off
	s_mov_b32 m0, s24
	v_readfirstlane_b32 s24, v12
	v_add_u32_e32 v12, 0x6000, v2
	global_load_lds_dwordx4 v[8:9], off
	v_lshl_add_u64 v[10:11], v[6:7], 0, 64
	s_mov_b32 m0, s24
	v_readfirstlane_b32 s24, v12
	v_add_u32_e32 v12, 0x8000, v2
	global_load_lds_dwordx4 v[10:11], off
	v_lshl_add_u64 v[10:11], v[8:9], 0, 64
	s_mov_b32 m0, s24
	v_readfirstlane_b32 s24, v12
	v_add_u32_e32 v12, 0xa000, v2
	global_load_lds_dwordx4 v[10:11], off
	v_lshl_add_u64 v[10:11], v[6:7], 0, s[92:93]
	s_mov_b32 m0, s24
	v_readfirstlane_b32 s24, v12
	global_load_lds_dwordx4 v[10:11], off
	v_lshl_add_u64 v[10:11], v[8:9], 0, s[92:93]
	s_mov_b32 m0, s24
	v_lshl_add_u64 v[6:7], v[6:7], 0, s[2:3]
	global_load_lds_dwordx4 v[10:11], off
	v_add_u32_e32 v10, 0xc000, v2
	v_add_u32_e32 v2, 0xe000, v2
	v_readfirstlane_b32 s24, v10
	s_mov_b32 m0, s24
	v_readfirstlane_b32 s24, v2
	global_load_lds_dwordx4 v[6:7], off
	v_lshl_add_u64 v[6:7], v[8:9], 0, s[2:3]
	s_mov_b32 m0, s24
	v_readfirstlane_b32 s24, v92
	global_load_lds_dwordx4 v[6:7], off
	s_waitcnt vmcnt(4)
	s_and_b32 s25, s24, 0xffffff00
	s_cmpk_lg_i32 s25, 0x100
	s_barrier
	s_cbranch_scc1 .LBB0_745
	s_barrier
	s_setprio 1

.LBB0_768:
	v_mov_b32_e32 v137, v200
	s_lshl_b64 s[30:31], s[90:91], 13
	v_ashrrev_i32_e32 v14, 6, v137
	v_bfe_u32 v4, v137, 2, 4
	v_lshlrev_b32_e32 v5, 5, v14
	v_or_b32_e32 v6, v5, v4
	v_ashrrev_i32_e32 v7, 31, v6
	v_lshrrev_b32_e32 v0, 4, v137
	v_lshlrev_b64 v[8:9], 13, v[6:7]
	v_or_b32_e32 v6, 16, v6
	s_waitcnt lgkmcnt(0)
	s_add_u32 s36, s28, s30
	v_xor_b32_e32 v0, v0, v137
	v_ashrrev_i32_e32 v7, 31, v6
	s_addc_u32 s37, s29, s31
	v_lshlrev_b32_e32 v2, 4, v0
	v_lshlrev_b64 v[6:7], 13, v[6:7]
	s_lshl_b32 s34, s25, 7
	v_and_b32_e32 v2, 48, v2
	v_lshl_add_u64 v[6:7], s[36:37], 0, v[6:7]
	s_and_b32 s34, s34, 0x380
	v_lshl_add_u64 v[10:11], v[6:7], 0, v[2:3]
	v_lshlrev_b32_e32 v6, 4, v14
	v_or_b32_e32 v7, s34, v4
	v_add_u32_e32 v12, v7, v6
	v_ashrrev_i32_e32 v13, 31, v12
	v_lshlrev_b64 v[12:13], 13, v[12:13]
	v_and_b32_e32 v1, 63, v137
	v_lshl_add_u64 v[8:9], s[36:37], 0, v[8:9]
	v_lshl_add_u64 v[12:13], s[48:49], 0, v[12:13]
	v_lshl_add_u64 v[8:9], v[8:9], 0, v[2:3]
	v_lshl_add_u64 v[12:13], v[12:13], 0, v[2:3]
	v_lshlrev_b32_e32 v2, 4, v1
	v_lshl_or_b32 v138, v14, 11, v2
	v_lshl_or_b32 v139, v14, 10, v2
	v_add_u32_e32 v7, 16, v138
	v_add_u32_e32 v14, 0x400, v7
	v_readfirstlane_b32 s36, v7
	v_add_u32_e32 v16, 16, v139
	s_mov_b32 m0, s36
	v_readfirstlane_b32 s36, v14
	v_add_u32_e32 v14, 0x4000, v16
	global_load_lds_dwordx4 v[8:9], off
	s_mov_b32 m0, s36
	v_readfirstlane_b32 s36, v14
	v_add_u32_e32 v17, 0x6000, v7
	global_load_lds_dwordx4 v[10:11], off
	s_mov_b32 m0, s36
	v_readfirstlane_b32 s36, v17
	v_add_u32_e32 v17, 0x6400, v7
	global_load_lds_dwordx4 v[12:13], off
	v_lshl_add_u64 v[14:15], v[8:9], 0, 64
	s_mov_b32 m0, s36
	v_readfirstlane_b32 s36, v17
	v_add_u32_e32 v16, 0xa000, v16
	global_load_lds_dwordx4 v[14:15], off
	v_lshl_add_u64 v[14:15], v[10:11], 0, 64
	s_mov_b32 m0, s36
	v_readfirstlane_b32 s36, v16
	v_add_u32_e32 v16, 0xc000, v7
	global_load_lds_dwordx4 v[14:15], off
	v_lshl_add_u64 v[14:15], v[12:13], 0, 64
	s_mov_b32 m0, s36
	v_readfirstlane_b32 s36, v16
	v_add_u32_e32 v7, 0xc400, v7
	global_load_lds_dwordx4 v[14:15], off
	v_lshl_add_u64 v[14:15], v[8:9], 0, s[92:93]
	s_mov_b32 m0, s36
	v_readfirstlane_b32 s36, v7
	v_add_u32_e32 v2, 0x4000, v139
	global_load_lds_dwordx4 v[14:15], off
	s_mov_b32 m0, s36
	s_add_i32 s36, 16, 0xc000
	v_add_u32_e32 v7, s36, v2
	v_readlane_b32 s37, v235, 50
	v_lshl_add_u64 v[14:15], v[10:11], 0, s[92:93]
	v_readfirstlane_b32 s36, v7
	v_add_u32_e32 v7, s37, v138
	global_load_lds_dwordx4 v[14:15], off
	v_lshl_add_u64 v[14:15], v[12:13], 0, s[92:93]
	s_mov_b32 m0, s36
	v_readfirstlane_b32 s36, v7
	v_add_u32_e32 v7, 0x400, v7
	global_load_lds_dwordx4 v[14:15], off
	v_lshl_add_u64 v[8:9], v[8:9], 0, s[2:3]
	s_mov_b32 m0, s36
	v_readfirstlane_b32 s36, v7
	v_add_u32_e32 v2, s37, v2
	global_load_lds_dwordx4 v[8:9], off
	v_lshl_add_u64 v[8:9], v[10:11], 0, s[2:3]
	s_mov_b32 m0, s36
	v_readfirstlane_b32 s36, v2
	global_load_lds_dwordx4 v[8:9], off
	v_lshl_add_u64 v[8:9], v[12:13], 0, s[2:3]
	s_mov_b32 m0, s36
	v_readfirstlane_b32 s36, v137
	global_load_lds_dwordx4 v[8:9], off
	s_waitcnt vmcnt(6)
	s_and_b32 s37, s36, 0xffffff00
	s_cmpk_lg_i32 s37, 0x100
	s_barrier
	s_cbranch_scc1 .LBB0_770
	s_barrier
	s_setprio 1

.LBB0_814:
	v_mov_b32_e32 v92, v200
	v_readlane_b32 s24, v236, 7
	v_ashrrev_i32_e32 v2, 6, v92
	v_bfe_u32 v4, v92, 2, 4
	v_lshlrev_b32_e32 v5, 4, v2
	v_lshrrev_b32_e32 v0, 4, v92
	v_or_b32_e32 v6, v5, v4
	v_xor_b32_e32 v0, v0, v92
	v_ashrrev_i32_e32 v7, 31, v6
	v_lshlrev_b64 v[8:9], 13, v[6:7]
	v_lshlrev_b32_e32 v7, 4, v0
	v_add_u32_e32 v6, s73, v6
	v_readlane_b32 s25, v236, 8
	s_add_u32 s24, s44, s24
	v_and_b32_e32 v10, 48, v7
	v_ashrrev_i32_e32 v7, 31, v6
	s_addc_u32 s25, s45, s25
	v_lshlrev_b64 v[6:7], 13, v[6:7]
	v_and_b32_e32 v1, 63, v92
	v_lshl_add_u64 v[8:9], s[24:25], 0, v[8:9]
	v_mov_b32_e32 v11, v3
	v_lshl_add_u64 v[6:7], s[48:49], 0, v[6:7]
	v_lshl_add_u64 v[8:9], v[8:9], 0, v[10:11]
	v_lshl_add_u64 v[6:7], v[6:7], 0, v[10:11]
	v_lshlrev_b32_e32 v10, 4, v1
	v_lshl_or_b32 v93, v2, 10, v10
	s_mov_b64 s[24:25], 0xaa08000
	v_add_u32_e32 v2, 16, v93
	v_lshl_add_u64 v[12:13], v[8:9], 0, s[24:25]
	v_readfirstlane_b32 s24, v2
	v_add_u32_e32 v10, 0x2000, v2
	s_mov_b32 m0, s24
	v_readfirstlane_b32 s24, v10
	global_load_lds_dwordx4 v[12:13], off
	s_mov_b32 m0, s24
	s_mov_b64 s[24:25], 0xaa08040
	v_add_u32_e32 v12, 0x4000, v2
	v_lshl_add_u64 v[10:11], v[8:9], 0, s[24:25]
	v_readfirstlane_b32 s24, v12
	v_add_u32_e32 v12, 0x6000, v2
	global_load_lds_dwordx4 v[6:7], off
	s_mov_b32 m0, s24
	v_readfirstlane_b32 s24, v12
	global_load_lds_dwordx4 v[10:11], off
	v_lshl_add_u64 v[10:11], v[6:7], 0, 64
	s_mov_b32 m0, s24
	s_mov_b64 s[24:25], 0xaa08080
	v_add_u32_e32 v12, 0x8000, v2
	global_load_lds_dwordx4 v[10:11], off
	v_lshl_add_u64 v[10:11], v[8:9], 0, s[24:25]
	v_readfirstlane_b32 s24, v12
	v_add_u32_e32 v12, 0xa000, v2
	s_mov_b32 m0, s24
	v_readfirstlane_b32 s24, v12
	global_load_lds_dwordx4 v[10:11], off
	v_lshl_add_u64 v[10:11], v[6:7], 0, s[92:93]
	s_mov_b32 m0, s24
	s_mov_b64 s[24:25], 0xaa080c0
	global_load_lds_dwordx4 v[10:11], off
	v_add_u32_e32 v10, 0xc000, v2
	v_lshl_add_u64 v[8:9], v[8:9], 0, s[24:25]
	v_readfirstlane_b32 s24, v10
	v_add_u32_e32 v2, 0xe000, v2
	s_mov_b32 m0, s24
	v_readfirstlane_b32 s24, v2
	global_load_lds_dwordx4 v[8:9], off
	v_lshl_add_u64 v[6:7], v[6:7], 0, s[2:3]
	s_mov_b32 m0, s24
	v_readfirstlane_b32 s24, v92
	global_load_lds_dwordx4 v[6:7], off
	s_waitcnt vmcnt(4)
	s_and_b32 s25, s24, 0xffffff00
	s_cmpk_lg_i32 s25, 0x100
	s_barrier
	s_cbranch_scc1 .LBB0_816
	s_barrier
	s_setprio 1

.LBB0_837:
	s_ashr_i32 s30, s50, 31
	s_lshr_b32 s30, s30, 29
	v_mov_b32_e32 v137, v200
	s_add_i32 s30, s50, s30
	s_ashr_i32 s34, s30, 3
	v_ashrrev_i32_e32 v14, 6, v137
	v_bfe_u32 v4, v137, 2, 4
	v_lshlrev_b32_e32 v5, 5, v14
	v_or_b32_e32 v2, v5, v4
	s_lshl_b32 s31, s34, 8
	v_add_u32_e32 v6, s31, v2
	v_ashrrev_i32_e32 v7, 31, v6
	v_lshrrev_b32_e32 v0, 4, v137
	v_lshlrev_b64 v[8:9], 11, v[6:7]
	v_or_b32_e32 v6, 16, v6
	s_and_b32 s30, s30, 0x1fffff8
	v_xor_b32_e32 v0, v0, v137
	v_ashrrev_i32_e32 v7, 31, v6
	s_sub_i32 s30, s50, s30
	v_lshlrev_b32_e32 v2, 4, v0
	v_lshlrev_b64 v[6:7], 11, v[6:7]
	v_and_b32_e32 v2, 48, v2
	v_lshl_add_u64 v[6:7], s[48:49], 0, v[6:7]
	s_lshl_b32 s30, s30, 7
	v_lshl_add_u64 v[10:11], v[6:7], 0, v[2:3]
	v_lshlrev_b32_e32 v6, 4, v14
	v_or_b32_e32 v7, s30, v4
	v_add_u32_e32 v12, v7, v6
	v_ashrrev_i32_e32 v13, 31, v12
	v_lshlrev_b64 v[12:13], 11, v[12:13]
	v_and_b32_e32 v1, 63, v137
	v_lshl_add_u64 v[8:9], s[48:49], 0, v[8:9]
	v_lshl_add_u64 v[12:13], s[46:47], 0, v[12:13]
	v_lshl_add_u64 v[8:9], v[8:9], 0, v[2:3]
	v_lshl_add_u64 v[12:13], v[12:13], 0, v[2:3]
	v_lshlrev_b32_e32 v2, 4, v1
	v_lshl_or_b32 v138, v14, 11, v2
	v_lshl_or_b32 v139, v14, 10, v2
	v_add_u32_e32 v7, 16, v138
	v_add_u32_e32 v14, 0x400, v7
	v_readfirstlane_b32 s35, v7
	v_add_u32_e32 v16, 16, v139
	s_mov_b32 m0, s35
	v_readfirstlane_b32 s35, v14
	v_add_u32_e32 v14, 0x4000, v16
	global_load_lds_dwordx4 v[8:9], off
	s_mov_b32 m0, s35
	v_readfirstlane_b32 s35, v14
	v_add_u32_e32 v17, 0x6000, v7
	global_load_lds_dwordx4 v[10:11], off
	s_mov_b32 m0, s35
	v_readfirstlane_b32 s35, v17
	v_add_u32_e32 v17, 0x6400, v7
	global_load_lds_dwordx4 v[12:13], off
	v_lshl_add_u64 v[14:15], v[8:9], 0, 64
	s_mov_b32 m0, s35
	v_readfirstlane_b32 s35, v17
	v_add_u32_e32 v16, 0xa000, v16
	global_load_lds_dwordx4 v[14:15], off
	v_lshl_add_u64 v[14:15], v[10:11], 0, 64
	s_mov_b32 m0, s35
	v_readfirstlane_b32 s35, v16
	v_add_u32_e32 v16, 0xc000, v7
	global_load_lds_dwordx4 v[14:15], off
	v_lshl_add_u64 v[14:15], v[12:13], 0, 64
	s_mov_b32 m0, s35
	v_readfirstlane_b32 s35, v16
	v_add_u32_e32 v7, 0xc400, v7
	global_load_lds_dwordx4 v[14:15], off
	v_lshl_add_u64 v[14:15], v[8:9], 0, s[92:93]
	s_mov_b32 m0, s35
	v_readfirstlane_b32 s35, v7
	v_add_u32_e32 v2, 0x4000, v139
	global_load_lds_dwordx4 v[14:15], off
	s_mov_b32 m0, s35
	s_add_i32 s35, 16, 0xc000
	v_add_u32_e32 v7, s35, v2
	v_readlane_b32 s36, v235, 50
	v_lshl_add_u64 v[14:15], v[10:11], 0, s[92:93]
	v_readfirstlane_b32 s35, v7
	v_add_u32_e32 v7, s36, v138
	global_load_lds_dwordx4 v[14:15], off
	v_lshl_add_u64 v[14:15], v[12:13], 0, s[92:93]
	s_mov_b32 m0, s35
	v_readfirstlane_b32 s35, v7
	v_add_u32_e32 v7, 0x400, v7
	global_load_lds_dwordx4 v[14:15], off
	v_lshl_add_u64 v[8:9], v[8:9], 0, s[2:3]
	s_mov_b32 m0, s35
	v_readfirstlane_b32 s35, v7
	v_add_u32_e32 v2, s36, v2
	global_load_lds_dwordx4 v[8:9], off
	v_lshl_add_u64 v[8:9], v[10:11], 0, s[2:3]
	s_mov_b32 m0, s35
	v_readfirstlane_b32 s35, v2
	global_load_lds_dwordx4 v[8:9], off
	v_lshl_add_u64 v[8:9], v[12:13], 0, s[2:3]
	s_mov_b32 m0, s35
	v_readfirstlane_b32 s51, v137
	global_load_lds_dwordx4 v[8:9], off
	s_waitcnt vmcnt(6)
	s_and_b32 s35, s51, 0xffffff00
	s_cmpk_lg_i32 s35, 0x100
	s_barrier
	s_cbranch_scc1 .LBB0_839
	s_barrier
	s_setprio 1

.LBB0_847:
	s_setprio 0
	s_cmpk_lt_u32 s51, 0x100
	s_cbranch_scc0 .LBB0_836
	s_barrier
	s_branch .LBB0_836

.LBB0_1121:
	s_mul_hi_i32 s42, s46, 0x2aaaaaab
	s_lshr_b32 s36, s42, 31
	s_add_i32 s42, s42, s36
	s_lshl_b32 s36, s42, 3
	s_or_b32 s43, s36, s83
	s_and_b64 s[36:37], s[74:75], exec
	v_mov_b32_e32 v0, v200
	s_mul_i32 s37, s42, 6
	s_cselect_b32 s36, s43, s42
	v_ashrrev_i32_e32 v6, 6, v0
	s_sub_i32 s37, s46, s37
	v_bfe_u32 v4, v0, 2, 4
	v_lshlrev_b32_e32 v5, 5, v6
	v_and_b32_e32 v1, 63, v0
	v_or_b32_e32 v7, v5, v4
	s_lshl_b32 s47, s36, 8
	s_lshl_b32 s36, s37, 8
	s_load_dwordx2 s[80:81], s[22:23], 0x90
	s_waitcnt lgkmcnt(0)
	v_bfe_u32 v176, v200, 6, 2
	v_bfe_u32 v177, v200, 5, 1
	v_lshlrev_b32_e32 v176, 6, v176
	v_lshl_or_b32 v176, v177, 2, v176
	v_add_u32_e32 v176, s36, v176
	v_lshlrev_b32_e32 v176, 2, v176
	global_load_dwordx4 v[144:147], v176, s[80:81]
	global_load_dwordx4 v[148:151], v176, s[80:81] offset:32
	global_load_dwordx4 v[152:155], v176, s[80:81] offset:64
	global_load_dwordx4 v[156:159], v176, s[80:81] offset:96
	global_load_dwordx4 v[160:163], v176, s[80:81] offset:128
	global_load_dwordx4 v[164:167], v176, s[80:81] offset:160
	global_load_dwordx4 v[168:171], v176, s[80:81] offset:192
	global_load_dwordx4 v[172:175], v176, s[80:81] offset:224
	v_lshrrev_b32_e32 v2, 4, v0
	v_add_u32_e32 v8, s47, v7
	v_or_b32_e32 v14, 16, v7
	v_add_u32_e32 v12, s36, v7
	v_lshlrev_b32_e32 v7, 4, v1
	v_xor_b32_e32 v2, v2, v0
	v_ashrrev_i32_e32 v9, 31, v8
	v_add_u32_e32 v10, s47, v14
	v_lshl_or_b32 v190, v6, 11, v7
	v_lshlrev_b64 v[8:9], 11, v[8:9]
	v_lshlrev_b32_e32 v2, 4, v2
	v_ashrrev_i32_e32 v11, 31, v10
	v_add_u32_e32 v7, 16, v190
	v_lshl_add_u64 v[8:9], s[26:27], 0, v[8:9]
	v_and_b32_e32 v2, 48, v2
	v_lshlrev_b64 v[10:11], 11, v[10:11]
	v_ashrrev_i32_e32 v13, 31, v12
	v_add_u32_e32 v14, s36, v14
	v_readfirstlane_b32 s37, v7
	v_add_u32_e32 v16, 0x400, v7
	v_lshl_add_u64 v[8:9], v[8:9], 0, v[2:3]
	v_lshl_add_u64 v[10:11], s[26:27], 0, v[10:11]
	v_lshlrev_b64 v[12:13], 11, v[12:13]
	v_ashrrev_i32_e32 v15, 31, v14
	s_mov_b32 m0, s37
	v_readfirstlane_b32 s37, v16
	v_add_u32_e32 v16, 0x4000, v7
	v_lshl_add_u64 v[10:11], v[10:11], 0, v[2:3]
	v_lshl_add_u64 v[12:13], s[24:25], 0, v[12:13]
	v_lshlrev_b64 v[14:15], 11, v[14:15]
	global_load_lds_dwordx4 v[8:9], off
	s_mov_b32 m0, s37
	v_readfirstlane_b32 s37, v16
	v_add_u32_e32 v16, 0x4400, v7
	v_lshl_add_u64 v[12:13], v[12:13], 0, v[2:3]
	v_lshl_add_u64 v[14:15], s[24:25], 0, v[14:15]
	global_load_lds_dwordx4 v[10:11], off
	s_mov_b32 m0, s37
	v_readfirstlane_b32 s37, v16
	v_add_u32_e32 v18, 0x8000, v7
	v_lshl_add_u64 v[14:15], v[14:15], 0, v[2:3]
	global_load_lds_dwordx4 v[12:13], off
	s_mov_b32 m0, s37
	v_readfirstlane_b32 s37, v18
	v_add_u32_e32 v18, 0x8400, v7
	global_load_lds_dwordx4 v[14:15], off
	v_lshl_add_u64 v[16:17], v[8:9], 0, 64
	s_mov_b32 m0, s37
	v_readfirstlane_b32 s37, v18
	v_add_u32_e32 v18, 0xc000, v7
	global_load_lds_dwordx4 v[16:17], off
	v_lshl_add_u64 v[16:17], v[10:11], 0, 64
	s_mov_b32 m0, s37
	v_readfirstlane_b32 s37, v18
	v_add_u32_e32 v7, 0xc400, v7
	global_load_lds_dwordx4 v[16:17], off
	v_lshl_add_u64 v[16:17], v[12:13], 0, 64
	s_mov_b32 m0, s37
	v_readfirstlane_b32 s37, v7
	global_load_lds_dwordx4 v[16:17], off
	s_mov_b32 m0, s37
	s_add_i32 s37, 16, 0x10000
	v_add_u32_e32 v7, s37, v190
	v_lshl_add_u64 v[16:17], v[14:15], 0, 64
	v_readfirstlane_b32 s37, v7
	global_load_lds_dwordx4 v[16:17], off
	v_lshl_add_u64 v[8:9], v[8:9], 0, s[92:93]
	s_mov_b32 m0, s37
	s_nop 0
	global_load_lds_dwordx4 v[8:9], off
	v_lshl_add_u64 v[8:9], v[10:11], 0, s[92:93]
	v_add_u32_e32 v10, 0x400, v7
	s_nop 0
	v_readfirstlane_b32 s37, v10
	v_add_u32_e32 v10, 0x4000, v7
	s_mov_b32 m0, s37
	v_readfirstlane_b32 s37, v10
	v_add_u32_e32 v7, 0x4400, v7
	global_load_lds_dwordx4 v[8:9], off
	v_lshl_add_u64 v[8:9], v[12:13], 0, s[92:93]
	s_mov_b32 m0, s37
	v_readfirstlane_b32 s37, v7
	global_load_lds_dwordx4 v[8:9], off
	v_lshl_add_u64 v[8:9], v[14:15], 0, s[92:93]
	s_mov_b32 m0, s37
	v_readfirstlane_b32 s37, v0
	global_load_lds_dwordx4 v[8:9], off
	s_waitcnt vmcnt(8)
	s_and_b32 s43, s37, 0xffffff00
	s_cmpk_lg_i32 s43, 0x100
	s_barrier
	s_cbranch_scc1 .LBB0_1123
	s_barrier
	s_setprio 1

.LBB0_1270:
	v_mov_b32_e32 v137, v200
	s_and_b32 s28, s36, 56
	s_or_b32 s28, s28, s83
	v_ashrrev_i32_e32 v14, 6, v137
	v_bfe_u32 v4, v137, 2, 4
	v_lshlrev_b32_e32 v5, 5, v14
	v_or_b32_e32 v2, v5, v4
	s_lshl_b32 s50, s28, 8
	v_add_u32_e32 v6, s50, v2
	v_ashrrev_i32_e32 v7, 31, v6
	v_lshrrev_b32_e32 v0, 4, v137
	v_lshlrev_b64 v[8:9], 11, v[6:7]
	v_or_b32_e32 v6, 16, v6
	v_xor_b32_e32 v0, v0, v137
	v_ashrrev_i32_e32 v7, 31, v6
	v_lshlrev_b32_e32 v2, 4, v0
	v_lshlrev_b64 v[6:7], 11, v[6:7]
	s_lshl_b32 s28, s36, 7
	v_and_b32_e32 v2, 48, v2
	v_lshl_add_u64 v[6:7], s[48:49], 0, v[6:7]
	s_and_b32 s37, s28, 0x380
	v_lshl_add_u64 v[10:11], v[6:7], 0, v[2:3]
	v_lshlrev_b32_e32 v6, 4, v14
	v_or_b32_e32 v7, s37, v4
	v_add_u32_e32 v12, v7, v6
	v_ashrrev_i32_e32 v13, 31, v12
	v_lshlrev_b64 v[12:13], 11, v[12:13]
	v_and_b32_e32 v1, 63, v137
	v_lshl_add_u64 v[8:9], s[48:49], 0, v[8:9]
	v_lshl_add_u64 v[12:13], s[46:47], 0, v[12:13]
	v_lshl_add_u64 v[8:9], v[8:9], 0, v[2:3]
	v_lshl_add_u64 v[12:13], v[12:13], 0, v[2:3]
	v_lshlrev_b32_e32 v2, 4, v1
	v_lshl_or_b32 v138, v14, 11, v2
	v_lshl_or_b32 v139, v14, 10, v2
	v_add_u32_e32 v7, 16, v138
	v_add_u32_e32 v14, 0x400, v7
	v_readfirstlane_b32 s28, v7
	v_add_u32_e32 v16, 16, v139
	s_mov_b32 m0, s28
	v_readfirstlane_b32 s28, v14
	v_add_u32_e32 v14, 0x4000, v16
	global_load_lds_dwordx4 v[8:9], off
	s_mov_b32 m0, s28
	v_readfirstlane_b32 s28, v14
	v_add_u32_e32 v17, 0x6000, v7
	global_load_lds_dwordx4 v[10:11], off
	s_mov_b32 m0, s28
	v_readfirstlane_b32 s28, v17
	v_add_u32_e32 v17, 0x6400, v7
	global_load_lds_dwordx4 v[12:13], off
	v_lshl_add_u64 v[14:15], v[8:9], 0, 64
	s_mov_b32 m0, s28
	v_readfirstlane_b32 s28, v17
	v_add_u32_e32 v16, 0xa000, v16
	global_load_lds_dwordx4 v[14:15], off
	v_lshl_add_u64 v[14:15], v[10:11], 0, 64
	s_mov_b32 m0, s28
	v_readfirstlane_b32 s28, v16
	v_add_u32_e32 v16, 0xc000, v7
	global_load_lds_dwordx4 v[14:15], off
	v_lshl_add_u64 v[14:15], v[12:13], 0, 64
	s_mov_b32 m0, s28
	v_readfirstlane_b32 s28, v16
	v_add_u32_e32 v7, 0xc400, v7
	global_load_lds_dwordx4 v[14:15], off
	v_lshl_add_u64 v[14:15], v[8:9], 0, s[92:93]
	s_mov_b32 m0, s28
	v_readfirstlane_b32 s28, v7
	v_add_u32_e32 v2, 0x4000, v139
	global_load_lds_dwordx4 v[14:15], off
	s_mov_b32 m0, s28
	s_add_i32 s28, 16, 0xc000
	v_add_u32_e32 v7, s28, v2
	v_readlane_b32 s29, v235, 50
	v_lshl_add_u64 v[14:15], v[10:11], 0, s[92:93]
	v_readfirstlane_b32 s28, v7
	v_add_u32_e32 v7, s29, v138
	global_load_lds_dwordx4 v[14:15], off
	v_lshl_add_u64 v[14:15], v[12:13], 0, s[92:93]
	s_mov_b32 m0, s28
	v_readfirstlane_b32 s28, v7
	v_add_u32_e32 v7, 0x400, v7
	global_load_lds_dwordx4 v[14:15], off
	v_lshl_add_u64 v[8:9], v[8:9], 0, s[2:3]
	s_mov_b32 m0, s28
	v_readfirstlane_b32 s28, v7
	v_add_u32_e32 v2, s29, v2
	global_load_lds_dwordx4 v[8:9], off
	v_lshl_add_u64 v[8:9], v[10:11], 0, s[2:3]
	s_mov_b32 m0, s28
	v_readfirstlane_b32 s28, v2
	global_load_lds_dwordx4 v[8:9], off
	v_lshl_add_u64 v[8:9], v[12:13], 0, s[2:3]
	s_mov_b32 m0, s28
	v_readfirstlane_b32 s51, v137
	global_load_lds_dwordx4 v[8:9], off
	s_waitcnt vmcnt(6)
	s_and_b32 s28, s51, 0xffffff00
	s_cmpk_lg_i32 s28, 0x100
	s_barrier
	s_cbranch_scc1 .LBB0_1272
	s_barrier
	s_setprio 1

.LBB0_1289:
	v_mov_b32_e32 v92, v200
	v_readlane_b32 s26, v236, 6
	v_ashrrev_i32_e32 v2, 6, v92
	v_bfe_u32 v4, v92, 2, 4
	v_lshlrev_b32_e32 v5, 4, v2
	v_or_b32_e32 v10, v5, v4
	v_lshrrev_b32_e32 v0, 4, v92
	v_add_u32_e32 v6, s26, v10
	v_add_u32_e32 v10, s73, v10
	v_xor_b32_e32 v0, v0, v92
	v_ashrrev_i32_e32 v7, 31, v6
	v_ashrrev_i32_e32 v11, 31, v10
	v_lshlrev_b64 v[6:7], 11, v[6:7]
	v_lshlrev_b32_e32 v8, 4, v0
	v_lshlrev_b64 v[10:11], 11, v[10:11]
	v_and_b32_e32 v1, 63, v92
	v_lshl_add_u64 v[6:7], s[48:49], 0, v[6:7]
	v_and_b32_e32 v8, 48, v8
	v_mov_b32_e32 v9, v3
	v_lshl_add_u64 v[10:11], s[46:47], 0, v[10:11]
	v_lshl_add_u64 v[6:7], v[6:7], 0, v[8:9]
	v_lshl_add_u64 v[8:9], v[10:11], 0, v[8:9]
	v_lshlrev_b32_e32 v10, 4, v1
	v_lshl_or_b32 v93, v2, 10, v10
	v_add_u32_e32 v2, 16, v93
	v_add_u32_e32 v10, 0x2000, v2
	v_readfirstlane_b32 s26, v2
	s_mov_b32 m0, s26
	v_readfirstlane_b32 s26, v10
	v_add_u32_e32 v12, 0x4000, v2
	global_load_lds_dwordx4 v[6:7], off
	s_mov_b32 m0, s26
	v_readfirstlane_b32 s26, v12
	v_add_u32_e32 v12, 0x6000, v2
	global_load_lds_dwordx4 v[8:9], off
	v_lshl_add_u64 v[10:11], v[6:7], 0, 64
	s_mov_b32 m0, s26
	v_readfirstlane_b32 s26, v12
	v_add_u32_e32 v12, 0x8000, v2
	global_load_lds_dwordx4 v[10:11], off
	v_lshl_add_u64 v[10:11], v[8:9], 0, 64
	s_mov_b32 m0, s26
	v_readfirstlane_b32 s26, v12
	v_add_u32_e32 v12, 0xa000, v2
	global_load_lds_dwordx4 v[10:11], off
	v_lshl_add_u64 v[10:11], v[6:7], 0, s[92:93]
	s_mov_b32 m0, s26
	v_readfirstlane_b32 s26, v12
	global_load_lds_dwordx4 v[10:11], off
	v_lshl_add_u64 v[10:11], v[8:9], 0, s[92:93]
	s_mov_b32 m0, s26
	v_lshl_add_u64 v[6:7], v[6:7], 0, s[2:3]
	global_load_lds_dwordx4 v[10:11], off
	v_add_u32_e32 v10, 0xc000, v2
	v_add_u32_e32 v2, 0xe000, v2
	v_readfirstlane_b32 s26, v10
	s_mov_b32 m0, s26
	v_readfirstlane_b32 s26, v2
	global_load_lds_dwordx4 v[6:7], off
	v_lshl_add_u64 v[6:7], v[8:9], 0, s[2:3]
	s_mov_b32 m0, s26
	v_readfirstlane_b32 s34, v92
	global_load_lds_dwordx4 v[6:7], off
	s_waitcnt vmcnt(4)
	s_and_b32 s26, s34, 0xffffff00
	s_cmpk_lg_i32 s26, 0x100
	s_barrier
	s_cbranch_scc1 .LBB0_1291
	s_barrier
	s_setprio 1

.LBB0_1305:
	s_setprio 0
	s_cmpk_lt_u32 s34, 0x100
	s_cbranch_scc0 .LBB0_1307
	s_barrier
